# attention loop: early K-tile loads moved off the critical vector segments to the tails of the matrix segments (behind the K-tile LDS write), on top of the out-of-line rescale paths
# speedup vs baseline: 1.0094x; 1.0094x over previous
; #define SBAR() __builtin_amdgcn_sched_barrier(0)
; #define VMW() asm volatile("s_waitcnt vmcnt(0)" ::: "memory")
; #define SLOAD_H(Kp, Vp, k0) do { S.st_v0 = load8(ROW(Vp, k0, sr)); S.st_v1 = load8(ROW(Vp, k0, 32 + sr));              \
;                          S.st_k0 = load8(ROW(Kp, k0, sr)); S.st_k1 = load8(ROW(Kp, k0, 32 + sr)); } while (0)
; #define SWRITE_HV(bf) do { *(bf16x8*)(V_lds + (bf) * SHM_V + vst0) = S.st_v0; *(bf16x8*)(V_lds + (bf) * SHM_V + vst1) = S.st_v1; } while (0)
; #define SWRITE_H(bf) do { SWRITE_HV(bf); SWRITE_HK(bf); } while (0)
; #define MASKT(P0_, P1_) sel_mask_tile(P0_, P1_, mw.x, mw.y, hi)
; template <int KB>
; __device__ __forceinline__ void qkt(f32x16& p0, f32x16& p1, const char* K_lds, int r32, int hi, const bf16x8* qr) {
;     p0 = f32x16{}; p1 = f32x16{};
;     const char* kb[4];
; #pragma unroll
;     for (int dd = 0; dd < 4; ++dd) kb[dd] = K_lds + KB * SHM_K + KSWZ(r32, (dd * 16 + hi * 8) * 2);
; #pragma unroll
;     for (int d0 = 0; d0 < 8; ++d0) { const char* a = kb[d0 & 3] + (d0 >> 2) * 128;
;         bf16x8 b0 = *reinterpret_cast<const bf16x8*>(a);
;         bf16x8 b1 = *reinterpret_cast<const bf16x8*>(a + 32 * 256);
;         p0 = __builtin_amdgcn_mfma_f32_32x32x16_bf16(b0, qr[d0], p0, 0, 0, 0);
;         p1 = __builtin_amdgcn_mfma_f32_32x32x16_bf16(b1, qr[d0], p1, 0, 0, 0); }
; __device__ __forceinline__ void attn_block(const BlockRef& cur, const BlockRef& nxt, char* lds, Seam& S) {
;     ...
;     SWRITE_HV(0); SBAR();
;     mw = LDMASK(0);
;     if (NT > 1) { SLOAD_H(Kh, Vh, KBASE(1)); }
;     SBAR(); qkt<0>(pA0, pA1, K_lds, r32, hi, S.qr);
;     MASKT(pA0, pA1); partialSM(pA0, pA1, m_reg, mnA, alA);
;     if (NT > 1) { VMW(); SWRITE_H(1); }
;     __syncthreads();
.LBB0_1298:
	v_readfirstlane_b32 s83, v0
	s_lshr_b32 s12, s38, 6
	s_or_b32 s81, s12, 3
	s_and_b32 s12, s83, 0x3fffffc0
	s_lshl_b32 s12, s12, 2
	s_add_i32 s84, s12, 0
	s_lshr_b32 s12, s83, 1
	s_and_b32 s12, s12, 0x7fffffe0
	v_and_b32_e32 v88, 31, v0
	v_or_b32_e32 v186, s12, v88
	s_mov_b32 s82, 1
	v_lshlrev_b32_e32 v165, 9, v186
	s_add_i32 s84, s84, 0x10000
	s_waitcnt vmcnt(1)
	ds_write_b128 v197, v[130:133]
	s_waitcnt vmcnt(0)
	ds_write_b128 v198, v[134:137]
	v_mov_b32_e32 v183, v167
	v_lshl_add_u64 v[2:3], s[70:71], 0, v[182:183]
	v_mov_b32_e32 v177, v167
	v_mov_b32_e32 v185, v167
	v_lshl_add_u64 v[2:3], v[2:3], 0, v[176:177]
	v_lshl_add_u64 v[4:5], s[70:71], 0, v[184:185]
	global_load_dwordx2 v[86:87], v165, s[68:69]
	v_lshl_add_u64 v[4:5], v[4:5], 0, v[176:177]
	global_load_dwordx4 v[50:53], v[2:3], off
	global_load_dwordx4 v[54:57], v[4:5], off
	v_lshl_add_u64 v[2:3], s[6:7], 0, v[182:183]
	v_lshl_add_u64 v[2:3], v[2:3], 0, v[176:177]
	v_lshl_add_u64 v[4:5], s[6:7], 0, v[184:185]
	v_lshl_add_u64 v[4:5], v[4:5], 0, v[176:177]
	global_load_dwordx4 v[58:61], v[2:3], off
	global_load_dwordx4 v[62:65], v[4:5], off
	ds_read_b128 v[2:5], v199 offset:32768
	ds_read_b128 v[6:9], v199 offset:32896
	s_mov_b32 s36, s13
	s_mov_b32 s37, s13
	s_mov_b32 s38, s13
	s_waitcnt lgkmcnt(1)
	v_mfma_f32_32x32x16_bf16 v[34:49], v[2:5], v[126:129], 0
	ds_read_b128 v[2:5], v199 offset:40960
	ds_read_b128 v[10:13], v199 offset:41088
	s_mov_b32 s39, s13
	s_mov_b32 s40, s13
	s_mov_b32 s41, s13
	s_mov_b32 s42, s13
	s_mov_b32 s43, s13
	s_mov_b32 s44, s13
	s_waitcnt lgkmcnt(1)
	v_mfma_f32_32x32x16_bf16 v[18:33], v[2:5], v[126:129], 0
	ds_read_b128 v[2:5], v200 offset:32768
	ds_read_b128 v[14:17], v200 offset:32896
	s_mov_b32 s45, s13
	s_mov_b32 s46, s13
	s_mov_b32 s47, s13
	s_mov_b32 s48, s13
	s_mov_b32 s49, s13
	s_mov_b32 s50, s13
	s_waitcnt lgkmcnt(1)
	v_mfma_f32_32x32x16_bf16 v[34:49], v[2:5], v[122:125], v[34:49]
	ds_read_b128 v[2:5], v200 offset:40960
	ds_read_b128 v[66:69], v200 offset:41088
	s_mov_b32 s51, s13
	v_lshl_add_u32 v185, v88, 2, s84
	v_lshl_add_u32 v183, v163, 2, s84
	v_add_u32_e32 v188, v170, v252
	s_mov_b64 s[16:17], s[70:71]
	s_mov_b64 s[100:101], s[6:7]
	v_mov_b32_e32 v205, 0
	s_waitcnt lgkmcnt(1)
	v_mfma_f32_32x32x16_bf16 v[18:33], v[2:5], v[122:125], v[18:33]
	ds_read_b128 v[2:5], v201 offset:32768
	ds_read_b128 v[70:73], v201 offset:32896
	s_waitcnt lgkmcnt(1)
	v_mfma_f32_32x32x16_bf16 v[34:49], v[2:5], v[118:121], v[34:49]
	ds_read_b128 v[2:5], v201 offset:40960
	ds_read_b128 v[74:77], v201 offset:41088
	s_waitcnt lgkmcnt(1)
	v_mfma_f32_32x32x16_bf16 v[18:33], v[2:5], v[118:121], v[18:33]
	ds_read_b128 v[2:5], v202 offset:32768
	ds_read_b128 v[78:81], v202 offset:32896
	s_waitcnt lgkmcnt(1)
	v_mfma_f32_32x32x16_bf16 v[34:49], v[2:5], v[114:117], v[34:49]
	ds_read_b128 v[2:5], v202 offset:40960
	ds_read_b128 v[82:85], v202 offset:41088
	s_waitcnt vmcnt(0)
	s_waitcnt vmcnt(3)
	ds_write_b128 v197, v[50:53] offset:16384
	s_waitcnt vmcnt(2)
	ds_write_b128 v198, v[54:57] offset:16384
	s_waitcnt vmcnt(1)
	ds_write_b128 v204, v[58:61] offset:49152
	s_waitcnt vmcnt(0)
	ds_write_b128 v204, v[62:65] offset:57344
	s_waitcnt lgkmcnt(0)
	s_barrier
	v_mfma_f32_32x32x16_bf16 v[34:49], v[6:9], v[110:113], v[34:49]
	v_mfma_f32_32x32x16_bf16 v[18:33], v[2:5], v[114:117], v[18:33]
	v_mfma_f32_32x32x16_bf16 v[34:49], v[14:17], v[106:109], v[34:49]
	v_mfma_f32_32x32x16_bf16 v[18:33], v[10:13], v[110:113], v[18:33]
	v_mov_b64_e32 v[2:3], s[36:37]
	v_mov_b64_e32 v[4:5], s[38:39]
	v_mov_b64_e32 v[6:7], s[40:41]
	v_mov_b64_e32 v[8:9], s[42:43]
	v_mov_b64_e32 v[10:11], s[44:45]
	v_mov_b64_e32 v[12:13], s[46:47]
	v_mov_b64_e32 v[14:15], s[48:49]
	v_mfma_f32_32x32x16_bf16 v[34:49], v[70:73], v[102:105], v[34:49]
	v_mov_b64_e32 v[16:17], s[50:51]
	v_mov_b64_e32 v[64:65], v[16:17]
	v_mov_b64_e32 v[62:63], v[14:15]
	v_mov_b64_e32 v[60:61], v[12:13]
	v_mov_b64_e32 v[58:59], v[10:11]
	v_mov_b64_e32 v[56:57], v[8:9]
	v_mov_b64_e32 v[54:55], v[6:7]
	v_mfma_f32_32x32x16_bf16 v[18:33], v[66:69], v[106:109], v[18:33]
	v_lshrrev_b32_e32 v66, v163, v86
	v_bfe_i32 v68, v66, 0, 1
	v_lshrrev_b32_e32 v67, v163, v87
	v_bfe_i32 v69, v67, 0, 1
	v_bfe_i32 v70, v67, 2, 1
	v_bfe_i32 v71, v67, 3, 1
	v_bfe_i32 v72, v67, 8, 1
	v_mfma_f32_32x32x16_bf16 v[34:49], v[78:81], v[98:101], v[34:49]
	v_bfe_i32 v73, v67, 9, 1
	v_bfe_i32 v78, v67, 18, 1
	v_bfe_i32 v79, v67, 19, 1
	v_bfe_i32 v80, v67, 24, 1
	v_bfe_i32 v81, v67, 25, 1
	v_mov_b64_e32 v[52:53], v[4:5]
	v_mov_b64_e32 v[50:51], v[2:3]
	v_mfma_f32_32x32x16_bf16 v[18:33], v[74:77], v[102:105], v[18:33]
	s_nop 3
	v_bitop3_b32 v68, v34, s74, v68 bitop3:0xe4
	v_bfe_i32 v34, v66, 1, 1
	v_bitop3_b32 v35, v35, s74, v34 bitop3:0xe4
	v_bfe_i32 v34, v66, 2, 1
	v_bitop3_b32 v36, v36, s74, v34 bitop3:0xe4
	v_bfe_i32 v34, v66, 3, 1
	v_bitop3_b32 v37, v37, s74, v34 bitop3:0xe4
	v_bfe_i32 v34, v66, 8, 1
	v_bitop3_b32 v38, v38, s74, v34 bitop3:0xe4
	v_bfe_i32 v34, v66, 9, 1
	v_bitop3_b32 v39, v39, s74, v34 bitop3:0xe4
	v_bfe_i32 v34, v66, 10, 1
	v_bitop3_b32 v40, v40, s74, v34 bitop3:0xe4
	v_bfe_i32 v34, v66, 11, 1
	v_mfma_f32_32x32x16_bf16 v[18:33], v[82:85], v[98:101], v[18:33]
	v_bitop3_b32 v41, v41, s74, v34 bitop3:0xe4
	v_bfe_i32 v34, v66, 16, 1
	v_bitop3_b32 v42, v42, s74, v34 bitop3:0xe4
	v_bfe_i32 v34, v66, 17, 1
	v_bitop3_b32 v43, v43, s74, v34 bitop3:0xe4
	v_bfe_i32 v34, v66, 18, 1
	v_bitop3_b32 v44, v44, s74, v34 bitop3:0xe4
	v_bfe_i32 v34, v66, 19, 1
	v_bitop3_b32 v45, v45, s74, v34 bitop3:0xe4
	v_bfe_i32 v34, v66, 24, 1
	v_bitop3_b32 v46, v46, s74, v34 bitop3:0xe4
	v_bfe_i32 v34, v66, 25, 1
	v_bitop3_b32 v47, v47, s74, v34 bitop3:0xe4
; __device__ __forceinline__ void partialSM(f32x16& p0, f32x16& p1, float& m_reg, float& mn, float& alpha) {
;     float pmax = p0[0];
; #pragma unroll
;     for (int r = 1; r < 16; ++r) pmax = fmaxf(pmax, p0[r]);
; #pragma unroll
;     for (int r = 0; r < 16; ++r) pmax = fmaxf(pmax, p1[r]);
;     { auto rr = __builtin_amdgcn_permlane32_swap(__float_as_uint(pmax), __float_as_uint(pmax), false, false);
;       pmax = fmaxf(__uint_as_float(rr[0]), __uint_as_float(rr[1])); }
;     constexpr float C2 = 1.4426950408889634f * SCALE;
;     if (__builtin_expect(__all((pmax - m_reg) * SCALE <= THR), 1)) { mn = m_reg; alpha = 1.f; }
;     else { mn = fmaxf(m_reg, pmax); alpha = __builtin_amdgcn_exp2f((m_reg - mn) * C2); m_reg = mn; }
;     const float mnL = -mn * C2;
; #pragma unroll
;     for (int r = 0; r < 16; ++r) p0[r] = fmaf(p0[r], C2, mnL);
; #pragma unroll
;     for (int r = 0; r < 16; ++r) p1[r] = fmaf(p1[r], C2, mnL);
; #pragma unroll
;     for (int r = 0; r < 16; ++r) p0[r] = __builtin_amdgcn_exp2f(p0[r]);
	v_bfe_i32 v34, v66, 26, 1
	v_bitop3_b32 v48, v48, s74, v34 bitop3:0xe4
	v_bfe_i32 v34, v66, 27, 1
	v_bitop3_b32 v18, v18, s74, v69 bitop3:0xe4
	v_bfe_i32 v69, v67, 1, 1
	v_bfe_i32 v74, v67, 10, 1
	v_bfe_i32 v75, v67, 11, 1
	v_bfe_i32 v76, v67, 16, 1
	v_bfe_i32 v77, v67, 17, 1
	v_bfe_i32 v82, v67, 26, 1
	v_bfe_i32 v66, v67, 27, 1
	v_bitop3_b32 v49, v49, s74, v34 bitop3:0xe4
	v_max_f32_e32 v34, v35, v35
	v_max_f32_e32 v67, v68, v68
	v_max_f32_e32 v34, v67, v34
	v_max3_f32 v34, v34, v36, v37
	v_max3_f32 v34, v34, v38, v39
	v_max3_f32 v34, v34, v40, v41
	v_max3_f32 v34, v34, v42, v43
	v_max3_f32 v34, v34, v44, v45
	v_max3_f32 v34, v34, v46, v47
	v_max3_f32 v34, v34, v48, v49
	v_bitop3_b32 v19, v19, s74, v69 bitop3:0xe4
	v_bitop3_b32 v20, v20, s74, v70 bitop3:0xe4
	v_max3_f32 v34, v34, v18, v19
	v_bitop3_b32 v21, v21, s74, v71 bitop3:0xe4
	v_bitop3_b32 v22, v22, s74, v72 bitop3:0xe4
	v_max3_f32 v34, v34, v20, v21
	v_bitop3_b32 v23, v23, s74, v73 bitop3:0xe4
	v_bitop3_b32 v24, v24, s74, v74 bitop3:0xe4
	v_max3_f32 v34, v34, v22, v23
	v_bitop3_b32 v25, v25, s74, v75 bitop3:0xe4
	v_bitop3_b32 v26, v26, s74, v76 bitop3:0xe4
	v_max3_f32 v34, v34, v24, v25
	v_bitop3_b32 v27, v27, s74, v77 bitop3:0xe4
	v_bitop3_b32 v28, v28, s74, v78 bitop3:0xe4
	v_max3_f32 v34, v34, v26, v27
	v_bitop3_b32 v29, v29, s74, v79 bitop3:0xe4
	v_bitop3_b32 v30, v30, s74, v80 bitop3:0xe4
	v_max3_f32 v34, v34, v28, v29
	v_bitop3_b32 v31, v31, s74, v81 bitop3:0xe4
	v_bitop3_b32 v32, v32, s74, v82 bitop3:0xe4
	v_max3_f32 v34, v34, v30, v31
	v_bitop3_b32 v33, v33, s74, v66 bitop3:0xe4
	v_max3_f32 v34, v34, v32, v33
	v_mov_b32_e32 v66, v34
	s_nop 1
	v_permlane32_swap_b32_e32 v34, v66
	v_max_f32_e32 v66, v66, v66
	v_max_f32_e32 v34, v34, v34
	v_max_f32_e32 v34, v34, v66
	v_add_f32_e32 v66, 0x7149f2ca, v34
	v_mul_f32_e32 v66, 0x3db504f3, v66
	v_max_f32_e32 v34, 0xf149f2ca, v34
	v_cmp_ge_f32_e32 vcc, s75, v66
	v_sub_f32_e32 v66, 0xf149f2ca, v34
	v_mul_f32_e32 v66, 0x3e0293ee, v66
	s_cmp_eq_u64 vcc, exec
	v_exp_f32_e32 v66, v66
	s_cselect_b64 vcc, -1, 0
	v_cndmask_b32_e32 v206, v34, v203, vcc
	v_mul_f32_e32 v34, 0xbe0293ee, v206
	v_mov_b32_e32 v67, v34
	v_cndmask_b32_e64 v177, v66, 1.0, vcc
	v_fmamk_f32 v66, v68, 0x3e0293ee, v34
	v_fmamk_f32 v35, v35, 0x3e0293ee, v34
	v_fmamk_f32 v36, v36, 0x3e0293ee, v34
	v_fmamk_f32 v37, v37, 0x3e0293ee, v34
	v_fmamk_f32 v38, v38, 0x3e0293ee, v34
	v_fmamk_f32 v39, v39, 0x3e0293ee, v34
	v_fmamk_f32 v40, v40, 0x3e0293ee, v34
	v_fmamk_f32 v41, v41, 0x3e0293ee, v34
	v_fmamk_f32 v42, v42, 0x3e0293ee, v34
	v_fmamk_f32 v43, v43, 0x3e0293ee, v34
	v_fmamk_f32 v44, v44, 0x3e0293ee, v34
	v_fmamk_f32 v45, v45, 0x3e0293ee, v34
	v_fmamk_f32 v46, v46, 0x3e0293ee, v34
	v_fmamk_f32 v47, v47, 0x3e0293ee, v34
	v_fmamk_f32 v48, v48, 0x3e0293ee, v34
	v_fmac_f32_e32 v67, 0x3e0293ee, v49
	v_exp_f32_e32 v219, v66
	v_exp_f32_e32 v220, v35
	v_exp_f32_e32 v221, v36
	v_exp_f32_e32 v222, v37
	v_exp_f32_e32 v223, v38
	v_exp_f32_e32 v225, v39
	v_exp_f32_e32 v224, v40
	v_exp_f32_e32 v226, v41
	v_exp_f32_e32 v211, v42
	v_exp_f32_e32 v212, v43
	v_exp_f32_e32 v213, v44
	v_exp_f32_e32 v215, v45
	v_exp_f32_e32 v214, v46
	v_exp_f32_e32 v216, v47
	v_exp_f32_e32 v217, v48
	v_exp_f32_e32 v218, v67
	s_lshl_b32 s36, s83, 8
	v_pk_fma_f32 v[152:153], v[32:33], s[14:15], v[34:35] op_sel_hi:[1,0,0]
	v_pk_fma_f32 v[156:157], v[30:31], s[14:15], v[34:35] op_sel_hi:[1,0,0]
	v_pk_fma_f32 v[160:161], v[28:29], s[14:15], v[34:35] op_sel_hi:[1,0,0]
	v_pk_fma_f32 v[150:151], v[26:27], s[14:15], v[34:35] op_sel_hi:[1,0,0]
	v_pk_fma_f32 v[154:155], v[24:25], s[14:15], v[34:35] op_sel_hi:[1,0,0]
	v_pk_fma_f32 v[158:159], v[22:23], s[14:15], v[34:35] op_sel_hi:[1,0,0]
	v_pk_fma_f32 v[192:193], v[20:21], s[14:15], v[34:35] op_sel_hi:[1,0,0]
	v_pk_fma_f32 v[194:195], v[18:19], s[14:15], v[34:35] op_sel_hi:[1,0,0]
	s_and_b32 s36, s36, 0xffffc000
	v_mov_b64_e32 v[48:49], v[16:17]
	v_mov_b64_e32 v[32:33], v[16:17]
	v_or_b32_e32 v179, s36, v254
	v_mov_b64_e32 v[46:47], v[14:15]
	v_mov_b64_e32 v[44:45], v[12:13]
	v_mov_b64_e32 v[42:43], v[10:11]
	v_mov_b64_e32 v[40:41], v[8:9]
	v_mov_b64_e32 v[38:39], v[6:7]
	v_mov_b64_e32 v[36:37], v[4:5]
	v_mov_b64_e32 v[34:35], v[2:3]
	v_mov_b64_e32 v[30:31], v[14:15]
	v_mov_b64_e32 v[28:29], v[12:13]
	v_mov_b64_e32 v[26:27], v[10:11]
	v_mov_b64_e32 v[24:25], v[8:9]
	v_mov_b64_e32 v[22:23], v[6:7]
	v_mov_b64_e32 v[20:21], v[4:5]
	v_mov_b64_e32 v[18:19], v[2:3]
	v_mul_f32_e32 v190, 0xbe0293ee, v206
	s_mov_b32 s76, 0
	v_readfirstlane_b32 s77, v0
	s_nop 3
	s_lshr_b32 s77, s77, 8
	s_cmp_eq_u32 s77, 0
	s_cbranch_scc1 .Lp5_lead
	s_barrier
.Lp5_lead:
	s_add_u32 s98, s100, 0x40000
	s_addc_u32 s99, s101, 0
	global_load_dwordx4 v[138:141], v188, s[98:99]
	s_add_u32 s98, s100, 0x50000
	s_addc_u32 s99, s101, 0
	global_load_dwordx4 v[142:145], v188, s[98:99]
; __device__ __forceinline__ void finishSM(f32x16& p0, f32x16& p1, float alpha, float& l_reg, bf16x8& pa0, bf16x8& pa1, bf16x8& pa2, bf16x8& pa3) {
; #pragma unroll
;     for (int r = 0; r < 16; ++r) p1[r] = __builtin_amdgcn_exp2f(p1[r]);
;     float ps = 0;
; #pragma unroll
;     for (int r = 0; r < 16; ++r) ps += p0[r];
; #pragma unroll
;     for (int r = 0; r < 16; ++r) ps += p1[r];
;     { auto rr = __builtin_amdgcn_permlane32_swap(__float_as_uint(ps), __float_as_uint(ps), false, false);
;       ps = __uint_as_float(rr[0]) + __uint_as_float(rr[1]); }
;     l_reg = l_reg * alpha + ps;
;     ...
;     PK4(p0, 0, pa0); PK4(p0, 8, pa1); PK4(p1, 0, pa2); PK4(p1, 8, pa3);
;     ...
; }
; template <int KB>
; __device__ __forceinline__ void qkt(f32x16& p0, f32x16& p1, const char* K_lds, int r32, int hi, const bf16x8* qr) {
;     p0 = f32x16{}; p1 = f32x16{};
;     const char* kb[4];
; #pragma unroll
;     for (int dd = 0; dd < 4; ++dd) kb[dd] = K_lds + KB * SHM_K + KSWZ(r32, (dd * 16 + hi * 8) * 2);
; #pragma unroll
;     for (int d0 = 0; d0 < 8; ++d0) { const char* a = kb[d0 & 3] + (d0 >> 2) * 128;
;         bf16x8 b0 = *reinterpret_cast<const bf16x8*>(a);
;         bf16x8 b1 = *reinterpret_cast<const bf16x8*>(a + 32 * 256);
;         p0 = __builtin_amdgcn_mfma_f32_32x32x16_bf16(b0, qr[d0], p0, 0, 0, 0);
;         p1 = __builtin_amdgcn_mfma_f32_32x32x16_bf16(b1, qr[d0], p1, 0, 0, 0); }
; }
; template <int VB>
; __device__ __forceinline__ void pv_tile(f32x16* o, int vb0, bf16x8 pa0, bf16x8 pa1, bf16x8 pa2, bf16x8 pa3) {
;     ...
;     PV_D0(0); PV_D0(1); PV_D0(2); PV_D0(3);
.LBB0_1299:
	v_exp_f32_e32 v209, v150
	v_add_f32_e32 v150, v220, v219
	v_add_f32_e32 v150, v221, v150
	v_add_f32_e32 v150, v222, v150
	v_add_f32_e32 v150, v223, v150
	v_add_f32_e32 v150, v225, v150
	v_add_f32_e32 v150, v224, v150
	v_add_f32_e32 v150, v226, v150
	v_add_f32_e32 v150, v211, v150
	v_add_f32_e32 v150, v212, v150
	v_exp_f32_e32 v194, v194
	v_exp_f32_e32 v195, v195
	v_exp_f32_e32 v192, v192
	v_exp_f32_e32 v193, v193
	v_exp_f32_e32 v158, v158
	v_exp_f32_e32 v159, v159
	v_exp_f32_e32 v207, v154
	v_exp_f32_e32 v208, v155
	v_exp_f32_e32 v210, v151
	v_exp_f32_e32 v160, v160
	v_exp_f32_e32 v161, v161
	v_exp_f32_e32 v227, v156
	v_cvt_pk_bf16_f32 v151, v224, v226
	v_cvt_pk_bf16_f32 v154, v214, v216
	v_cvt_pk_bf16_f32 v155, v217, v218
	v_cvt_pk_bf16_f32 v156, v194, v195
	v_exp_f32_e32 v228, v157
	v_exp_f32_e32 v229, v152
	v_exp_f32_e32 v230, v153
	v_cvt_pk_bf16_f32 v152, v211, v212
	v_cvt_pk_bf16_f32 v153, v213, v215
	v_cvt_pk_bf16_f32 v157, v192, v193
	v_cvt_pk_bf16_f32 v211, v229, v230
	v_add_f32_e32 v249, v213, v150
	v_add_f32_e32 v249, v215, v249
	v_add_f32_e32 v249, v214, v249
	v_add_f32_e32 v249, v216, v249
	v_add_f32_e32 v249, v217, v249
	v_add_f32_e32 v249, v218, v249
	v_add_f32_e32 v249, v194, v249
	v_add_f32_e32 v248, v195, v249
	v_add_f32_e32 v248, v192, v248
	v_add_f32_e32 v248, v193, v248
	v_add_f32_e32 v248, v158, v248
	v_add_f32_e32 v248, v159, v248
	v_add_f32_e32 v248, v207, v248
	v_add_f32_e32 v248, v208, v248
	v_add_f32_e32 v248, v209, v248
	v_add_f32_e32 v248, v210, v248
	v_add_f32_e32 v248, v160, v248
	v_add_f32_e32 v248, v161, v248
	v_add_f32_e32 v248, v227, v248
	v_add_f32_e32 v248, v228, v248
	v_add_f32_e32 v248, v229, v248
	v_add_f32_e32 v181, v230, v248
	v_cvt_pk_bf16_f32 v148, v219, v220
	v_cvt_pk_bf16_f32 v149, v221, v222
	v_cvt_pk_bf16_f32 v150, v223, v225
	v_cvt_pk_bf16_f32 v158, v158, v159
	v_cvt_pk_bf16_f32 v159, v207, v208
	v_cvt_pk_bf16_f32 v208, v209, v210
	v_cvt_pk_bf16_f32 v210, v227, v228
	v_cvt_pk_bf16_f32 v209, v160, v161
	s_waitcnt lgkmcnt(0)
	s_barrier
	s_cmp_eq_u32 s76, 0
	s_cbranch_scc1 .Lp5_vw_a
	s_waitcnt vmcnt(2)
	ds_write_b128 v197, v[130:133] offset:16384
	ds_write_b128 v198, v[134:137] offset:16384
.Lp5_vw_a:
	global_load_dwordx2 v[146:147], v179, s[68:69] offset:-8
	s_add_u32 s98, s16, 0x40000
	s_addc_u32 s99, s17, 0
	global_load_dwordx4 v[130:133], v188, s[98:99]
	s_add_u32 s98, s16, 0x50000
	s_addc_u32 s99, s17, 0
	global_load_dwordx4 v[134:137], v188, s[98:99]
	ds_read_b128 v[66:69], v199 offset:49152
	ds_read_b128 v[82:85], v199 offset:57344
	ds_read_b128 v[172:175], v200 offset:49152
	ds_read_b128 v[232:235], v200 offset:57344
	ds_read_b128 v[236:239], v201 offset:49152
	ds_read_b128 v[240:243], v201 offset:57344
	ds_read_b128 v[244:247], v202 offset:49152
	s_waitcnt lgkmcnt(6)
	v_mfma_f32_32x32x16_bf16 v[66:81], v[66:69], v[126:129], 0
	s_waitcnt lgkmcnt(5)
	v_mfma_f32_32x32x16_bf16 v[82:97], v[82:85], v[126:129], 0
	s_waitcnt lgkmcnt(4)
	v_mfma_f32_32x32x16_bf16 v[66:81], v[172:175], v[122:125], v[66:81]
	ds_read_b128 v[172:175], v202 offset:57344
	s_waitcnt lgkmcnt(4)
	v_mfma_f32_32x32x16_bf16 v[82:97], v[232:235], v[122:125], v[82:97]
	ds_read_b128 v[232:235], v199 offset:49280
	s_waitcnt lgkmcnt(4)
	v_mfma_f32_32x32x16_bf16 v[66:81], v[236:239], v[118:121], v[66:81]
	ds_read_b128 v[236:239], v199 offset:57472
	s_waitcnt lgkmcnt(4)
	v_mfma_f32_32x32x16_bf16 v[82:97], v[240:243], v[118:121], v[82:97]
	ds_read_b128 v[240:243], v200 offset:49280
	s_waitcnt lgkmcnt(4)
	v_mfma_f32_32x32x16_bf16 v[66:81], v[244:247], v[114:117], v[66:81]
	ds_read_b128 v[244:247], v200 offset:57472
	s_waitcnt lgkmcnt(4)
	v_mfma_f32_32x32x16_bf16 v[82:97], v[172:175], v[114:117], v[82:97]
	ds_read_b128 v[172:175], v201 offset:49280
	s_waitcnt lgkmcnt(4)
	v_mfma_f32_32x32x16_bf16 v[66:81], v[232:235], v[110:113], v[66:81]
	ds_read_b128 v[232:235], v201 offset:57472
	s_waitcnt lgkmcnt(4)
	v_mfma_f32_32x32x16_bf16 v[82:97], v[236:239], v[110:113], v[82:97]
	ds_read_b128 v[236:239], v202 offset:49280
	s_waitcnt lgkmcnt(4)
	v_mfma_f32_32x32x16_bf16 v[66:81], v[240:243], v[106:109], v[66:81]
	ds_read_b64_tr_b16 v[212:213], v1 offset:0x0
	ds_read_b64_tr_b16 v[214:215], v1 offset:0x800
	ds_read_b64_tr_b16 v[216:217], v1 offset:0x200
	ds_read_b64_tr_b16 v[218:219], v1 offset:0xa00
	ds_read_b64_tr_b16 v[220:221], v1 offset:0x400
	ds_read_b64_tr_b16 v[222:223], v1 offset:0xc00
	ds_read_b64_tr_b16 v[224:225], v1 offset:0x600
	ds_read_b64_tr_b16 v[226:227], v1 offset:0xe00
	ds_read_b128 v[240:243], v202 offset:57472
	s_waitcnt lgkmcnt(12)
	v_mfma_f32_32x32x16_bf16 v[82:97], v[244:247], v[106:109], v[82:97]
	s_waitcnt lgkmcnt(11)
	v_mfma_f32_32x32x16_bf16 v[66:81], v[172:175], v[102:105], v[66:81]
	s_waitcnt lgkmcnt(10)
	v_mfma_f32_32x32x16_bf16 v[82:97], v[232:235], v[102:105], v[82:97]
	s_waitcnt lgkmcnt(9)
	v_mfma_f32_32x32x16_bf16 v[66:81], v[236:239], v[98:101], v[66:81]
	s_waitcnt lgkmcnt(0)
	v_mfma_f32_32x32x16_bf16 v[82:97], v[240:243], v[98:101], v[82:97]
	ds_read_b64_tr_b16 v[248:249], v1 offset:0x1000
	ds_read_b64_tr_b16 v[250:251], v1 offset:0x1800
	ds_read_b64_tr_b16 v[172:173], v1 offset:0x1200
	ds_read_b64_tr_b16 v[174:175], v1 offset:0x1a00
	ds_read_b64_tr_b16 v[232:233], v1 offset:0x1400
	ds_read_b64_tr_b16 v[234:235], v1 offset:0x1c00
	s_waitcnt lgkmcnt(13)
	v_mfma_f32_32x32x16_bf16 v[2:17], v[148:151], v[212:215], v[2:17]
	ds_read_b64_tr_b16 v[236:237], v1 offset:0x1600
	ds_read_b64_tr_b16 v[238:239], v1 offset:0x1e00
	s_waitcnt lgkmcnt(13)
	v_mfma_f32_32x32x16_bf16 v[50:65], v[148:151], v[216:219], v[50:65]
	ds_read_b64_tr_b16 v[240:241], v1 offset:0x2000
	ds_read_b64_tr_b16 v[242:243], v1 offset:0x2800
	s_waitcnt lgkmcnt(13)
; __device__ __forceinline__ void sel_mask_tile(f32x16& p0, f32x16& p1, unsigned wlo, unsigned whi, int hi) {
;     const unsigned NEGB = 0xff800000u;
;     const unsigned lo = wlo >> (4 * hi), h2 = whi >> (4 * hi);
; #pragma unroll
;     for (int r = 0; r < 16; ++r) {
;         const int c = (r & 3) + 8 * (r >> 2);
;         const unsigned m0 = (unsigned)__builtin_amdgcn_sbfe((int)lo, c, 1), m1 = (unsigned)__builtin_amdgcn_sbfe((int)h2, c, 1);
;         p0[r] = __uint_as_float((__float_as_uint(p0[r]) & m0) | (NEGB & ~m0));
;         p1[r] = __uint_as_float((__float_as_uint(p1[r]) & m1) | (NEGB & ~m1));
;     }
; }
; __device__ __forceinline__ void partialSM(f32x16& p0, f32x16& p1, float& m_reg, float& mn, float& alpha) {
;     float pmax = p0[0];
; #pragma unroll
;     for (int r = 1; r < 16; ++r) pmax = fmaxf(pmax, p0[r]);
; #pragma unroll
;     for (int r = 0; r < 16; ++r) pmax = fmaxf(pmax, p1[r]);
;     { auto rr = __builtin_amdgcn_permlane32_swap(__float_as_uint(pmax), __float_as_uint(pmax), false, false);
;       pmax = fmaxf(__uint_as_float(rr[0]), __uint_as_float(rr[1])); }
;     constexpr float C2 = 1.4426950408889634f * SCALE;
;     if (__builtin_expect(__all((pmax - m_reg) * SCALE <= THR), 1)) { mn = m_reg; alpha = 1.f; }
; template <int VB>
; __device__ __forceinline__ void pv_tile(f32x16* o, int vb0, bf16x8 pa0, bf16x8 pa1, bf16x8 pa2, bf16x8 pa3) {
;     ...
;     PV_D0(0); PV_D0(1); PV_D0(2); PV_D0(3);
	v_mfma_f32_32x32x16_bf16 v[34:49], v[148:151], v[220:223], v[34:49]
	ds_read_b64_tr_b16 v[244:245], v1 offset:0x2200
	ds_read_b64_tr_b16 v[246:247], v1 offset:0x2a00
	s_waitcnt lgkmcnt(13)
	v_mfma_f32_32x32x16_bf16 v[18:33], v[148:151], v[224:227], v[18:33]
	ds_read_b64_tr_b16 v[224:225], v1 offset:0x2400
	ds_read_b64_tr_b16 v[226:227], v1 offset:0x2c00
	s_waitcnt lgkmcnt(12)
	v_mfma_f32_32x32x16_bf16 v[2:17], v[152:155], v[248:251], v[2:17]
	ds_read_b64_tr_b16 v[248:249], v1 offset:0x2600
	ds_read_b64_tr_b16 v[250:251], v1 offset:0x2e00
	s_waitcnt lgkmcnt(12)
	v_mfma_f32_32x32x16_bf16 v[50:65], v[152:155], v[172:175], v[50:65]
	ds_read_b64_tr_b16 v[172:173], v1 offset:0x3000
	ds_read_b64_tr_b16 v[174:175], v1 offset:0x3800
	s_waitcnt lgkmcnt(12)
	v_mfma_f32_32x32x16_bf16 v[34:49], v[152:155], v[232:235], v[34:49]
	ds_read_b64_tr_b16 v[232:233], v1 offset:0x3200
	ds_read_b64_tr_b16 v[234:235], v1 offset:0x3a00
	s_waitcnt lgkmcnt(12)
	v_mfma_f32_32x32x16_bf16 v[18:33], v[152:155], v[236:239], v[18:33]
	ds_read_b64_tr_b16 v[236:237], v1 offset:0x3400
	ds_read_b64_tr_b16 v[238:239], v1 offset:0x3c00
	s_waitcnt lgkmcnt(12)
	v_mfma_f32_32x32x16_bf16 v[2:17], v[156:159], v[240:243], v[2:17]
	ds_read_b64_tr_b16 v[240:241], v1 offset:0x3600
	ds_read_b64_tr_b16 v[242:243], v1 offset:0x3e00
	s_waitcnt lgkmcnt(12)
	v_mfma_f32_32x32x16_bf16 v[50:65], v[156:159], v[244:247], v[50:65]
	s_waitcnt lgkmcnt(10)
	v_mfma_f32_32x32x16_bf16 v[34:49], v[156:159], v[224:227], v[34:49]
	s_waitcnt lgkmcnt(8)
	v_mfma_f32_32x32x16_bf16 v[18:33], v[156:159], v[248:251], v[18:33]
	s_waitcnt lgkmcnt(6)
	v_mfma_f32_32x32x16_bf16 v[2:17], v[208:211], v[172:175], v[2:17]
	s_waitcnt lgkmcnt(4)
	v_mfma_f32_32x32x16_bf16 v[50:65], v[208:211], v[232:235], v[50:65]
	s_waitcnt lgkmcnt(2)
	v_mfma_f32_32x32x16_bf16 v[34:49], v[208:211], v[236:239], v[34:49]
	s_waitcnt lgkmcnt(0)
	v_mfma_f32_32x32x16_bf16 v[18:33], v[208:211], v[240:243], v[18:33]
	s_waitcnt vmcnt(3)
	ds_write_b128 v204, v[138:141] offset:32768
	ds_write_b128 v204, v[142:145] offset:40960
	s_add_i32 s98, s82, 2
	s_cmp_gt_u32 s98, s81
	s_cbranch_scc1 .Lp5_k2_skip
	s_add_u32 s98, s100, 0x60000
	s_addc_u32 s99, s101, 0
	global_load_dwordx4 v[138:141], v188, s[98:99]
	s_add_u32 s98, s100, 0x70000
	s_addc_u32 s99, s101, 0
	global_load_dwordx4 v[142:145], v188, s[98:99]
.Lp5_k2_done:
	s_waitcnt lgkmcnt(0)
	s_barrier
	s_nop 0
	s_waitcnt vmcnt(4)
	v_lshrrev_b32_e32 v160, v163, v146
	v_lshrrev_b32_e32 v161, v163, v147
	v_bfe_i32 v146, v160, 0, 1
	v_bfe_i32 v147, v161, 0, 1
	v_bitop3_b32 v146, v66, s74, v146 bitop3:0xe4
	v_bitop3_b32 v66, v82, s74, v147 bitop3:0xe4
	v_bfe_i32 v82, v160, 1, 1
	v_bfe_i32 v147, v161, 1, 1
	v_bitop3_b32 v82, v67, s74, v82 bitop3:0xe4
	v_bitop3_b32 v67, v83, s74, v147 bitop3:0xe4
	v_bfe_i32 v83, v160, 2, 1
	v_bfe_i32 v147, v161, 2, 1
	v_bitop3_b32 v83, v68, s74, v83 bitop3:0xe4
	v_bitop3_b32 v68, v84, s74, v147 bitop3:0xe4
	v_bfe_i32 v84, v160, 3, 1
	v_bfe_i32 v148, v161, 3, 1
	v_bitop3_b32 v147, v69, s74, v84 bitop3:0xe4
	v_bfe_i32 v84, v160, 8, 1
	v_bitop3_b32 v69, v85, s74, v148 bitop3:0xe4
	v_bfe_i32 v85, v161, 8, 1
	v_bitop3_b32 v148, v70, s74, v84 bitop3:0xe4
	v_bfe_i32 v84, v160, 9, 1
	v_bitop3_b32 v70, v86, s74, v85 bitop3:0xe4
	v_bfe_i32 v85, v161, 9, 1
	v_bitop3_b32 v149, v71, s74, v84 bitop3:0xe4
	v_bfe_i32 v84, v160, 10, 1
	v_bitop3_b32 v71, v87, s74, v85 bitop3:0xe4
	v_bfe_i32 v85, v161, 10, 1
	v_bitop3_b32 v87, v72, s74, v84 bitop3:0xe4
	v_bfe_i32 v84, v160, 11, 1
	v_bitop3_b32 v72, v88, s74, v85 bitop3:0xe4
	v_bfe_i32 v85, v161, 11, 1
	v_bitop3_b32 v88, v73, s74, v84 bitop3:0xe4
	v_bfe_i32 v73, v160, 16, 1
	v_bitop3_b32 v84, v89, s74, v85 bitop3:0xe4
	v_bfe_i32 v85, v161, 16, 1
	v_bitop3_b32 v89, v74, s74, v73 bitop3:0xe4
	v_bfe_i32 v73, v160, 17, 1
	v_bfe_i32 v74, v161, 17, 1
	v_bitop3_b32 v85, v90, s74, v85 bitop3:0xe4
	v_bitop3_b32 v90, v75, s74, v73 bitop3:0xe4
	v_bitop3_b32 v86, v91, s74, v74 bitop3:0xe4
	v_bfe_i32 v73, v160, 18, 1
	v_bfe_i32 v74, v161, 18, 1
	v_bitop3_b32 v91, v76, s74, v73 bitop3:0xe4
	v_bitop3_b32 v76, v92, s74, v74 bitop3:0xe4
	v_bfe_i32 v73, v160, 19, 1
	v_bfe_i32 v74, v161, 19, 1
	v_bitop3_b32 v92, v77, s74, v73 bitop3:0xe4
	v_bitop3_b32 v77, v93, s74, v74 bitop3:0xe4
	v_bfe_i32 v73, v160, 24, 1
	v_bfe_i32 v74, v161, 24, 1
	v_bitop3_b32 v93, v78, s74, v73 bitop3:0xe4
	v_bitop3_b32 v78, v94, s74, v74 bitop3:0xe4
	v_bfe_i32 v73, v160, 25, 1
	v_bfe_i32 v74, v161, 25, 1
	v_bitop3_b32 v79, v79, s74, v73 bitop3:0xe4
	v_bitop3_b32 v73, v95, s74, v74 bitop3:0xe4
	v_bfe_i32 v74, v160, 26, 1
	v_bfe_i32 v75, v161, 26, 1
	v_bitop3_b32 v80, v80, s74, v74 bitop3:0xe4
	v_bitop3_b32 v74, v96, s74, v75 bitop3:0xe4
	v_bfe_i32 v75, v160, 27, 1
	v_bfe_i32 v94, v161, 27, 1
	v_bitop3_b32 v81, v81, s74, v75 bitop3:0xe4
	v_bitop3_b32 v75, v97, s74, v94 bitop3:0xe4
	v_max_f32_e32 v94, v146, v82
	v_max3_f32 v94, v94, v83, v147
	v_max3_f32 v94, v94, v148, v149
	v_max3_f32 v94, v94, v87, v88
	v_max3_f32 v94, v94, v89, v90
	v_max3_f32 v94, v94, v91, v92
	v_max3_f32 v94, v94, v93, v79
	v_max3_f32 v94, v94, v80, v81
	v_max3_f32 v94, v94, v66, v67
	v_max3_f32 v94, v94, v68, v69
	v_max3_f32 v94, v94, v70, v71
	v_max3_f32 v94, v94, v72, v84
	v_max3_f32 v94, v94, v85, v86
	v_max3_f32 v94, v94, v76, v77
	v_max3_f32 v94, v94, v78, v73
	v_max3_f32 v94, v94, v74, v75
	v_mov_b32_e32 v95, v94
	s_nop 1
	v_permlane32_swap_b32_e32 v94, v95
	v_max_f32_e32 v94, v94, v95
	v_sub_f32_e32 v95, v94, v206
	v_mul_f32_e32 v95, 0x3db504f3, v95
	v_cmp_ge_f32_e32 vcc, s75, v95
	s_cmp_eq_u64 vcc, exec
	s_cselect_b64 s[6:7], -1, 0
	s_cbranch_scc0 .Lp5_y1_slow
	v_mov_b32_e32 v208, 1.0

.Lp5_kw2_skip:
	s_cmp_ge_u32 s82, s81
	s_cbranch_scc1 .Lp5_k1_skip
	s_add_u32 s98, s100, 0x80000
	s_addc_u32 s99, s101, 0
	global_load_dwordx4 v[138:141], v188, s[98:99]
	s_add_u32 s98, s100, 0x90000
	s_addc_u32 s99, s101, 0
	global_load_dwordx4 v[142:145], v188, s[98:99]
